# phase 0 w_in conversion: branch-free, two items per trip
# speedup vs baseline: 1.0011x; 1.0011x over previous
.LBB0_75:
	s_or_b64 exec, exec, s[10:11]
	s_mov_b32 s0, 0xb8000
	v_cmp_gt_i32_e32 vcc, s0, v2
	s_and_saveexec_b64 s[0:1], vcc
	s_cbranch_execz .LBB0_120
	s_mov_b64 s[2:3], 0
	s_mov_b32 s9, 0xb21642c9
	s_mov_b32 s10, 0xb100
	s_mov_b32 s34, 0xb7fff
	s_mov_b64 s[12:13], s[68:69]
	s_add_u32 s14, s12, 0x5880
	s_addc_u32 s15, s13, 0
	s_add_u32 s16, s14, 0x5880
	s_addc_u32 s17, s15, 0
	s_add_u32 s18, s16, 0x5880
	s_addc_u32 s19, s17, 0
	s_add_u32 s20, s18, 0x5880
	s_addc_u32 s21, s19, 0
	s_add_u32 s22, s20, 0x5880
	s_addc_u32 s23, s21, 0
	s_add_u32 s24, s22, 0x5880
	s_addc_u32 s25, s23, 0
	s_add_u32 s26, s24, 0x5880
	s_addc_u32 s27, s25, 0
	v_mov_b32_e32 v1, v2
.Lcv_loop:
	v_mul_hi_i32 v7, v1, s9
	v_add_u32_e32 v7, v7, v1
	v_lshrrev_b32_e32 v8, 31, v7
	v_ashrrev_i32_e32 v7, 12, v7
	v_add_u32_e32 v4, v7, v8
	v_mul_i32_i24_e32 v7, 0x1700, v4
	v_sub_u32_e32 v5, v1, v7
	v_mov_b32_e32 v6, 0
	v_mov_b32_e32 v7, 32
	v_cmp_lt_i32_e32 vcc, 0x3ff, v5
	s_nop 1
	v_cndmask_b32_e32 v6, v6, v7, vcc
	v_mov_b32_e32 v7, 0x620
	v_cmp_lt_i32_e32 vcc, 0x5ff, v5
	s_nop 1
	v_cndmask_b32_e32 v6, v6, v7, vcc
	v_mov_b32_e32 v7, 0xfffff620
	v_cmp_lt_i32_e32 vcc, 0xfff, v5
	s_nop 1
	v_cndmask_b32_e32 v6, v6, v7, vcc
	v_mov_b32_e32 v7, 0xffffee00
	v_cmp_lt_i32_e32 vcc, 0x15ff, v5
	s_nop 1
	v_cndmask_b32_e32 v6, v6, v7, vcc
	v_mov_b32_e32 v7, 0x1620
	v_cmp_gt_i32_e64 s[28:29], v7, v5
	v_add_u32_e32 v6, v5, v6
	s_nop 0
	v_cndmask_b32_e64 v6, 0, v6, s[28:29]
	v_mad_u32_u24 v9, v4, s10, v6
	v_lshlrev_b32_e32 v9, 2, v9
	v_lshlrev_b32_e32 v10, 11, v5
	v_lshl_add_u32 v10, v4, 4, v10
	global_load_dword v12, v9, s[12:13]
	global_load_dword v13, v9, s[14:15]
	global_load_dword v14, v9, s[16:17]
	global_load_dword v15, v9, s[18:19]
	global_load_dword v16, v9, s[20:21]
	global_load_dword v17, v9, s[22:23]
	global_load_dword v18, v9, s[24:25]
	global_load_dword v19, v9, s[26:27]
	v_add_u32_e32 v24, s8, v1
	v_cmp_ge_i32_e64 s[36:37], s34, v24
	s_nop 1
	v_cndmask_b32_e64 v25, v1, v24, s[36:37]
	v_mul_hi_i32 v29, v25, s9
	v_add_u32_e32 v29, v29, v25
	v_lshrrev_b32_e32 v30, 31, v29
	v_ashrrev_i32_e32 v29, 12, v29
	v_add_u32_e32 v26, v29, v30
	v_mul_i32_i24_e32 v29, 0x1700, v26
	v_sub_u32_e32 v27, v25, v29
	v_mov_b32_e32 v28, 0
	v_mov_b32_e32 v29, 32
	v_cmp_lt_i32_e32 vcc, 0x3ff, v27
	s_nop 1
	v_cndmask_b32_e32 v28, v28, v29, vcc
	v_mov_b32_e32 v29, 0x620
	v_cmp_lt_i32_e32 vcc, 0x5ff, v27
	s_nop 1
	v_cndmask_b32_e32 v28, v28, v29, vcc
	v_mov_b32_e32 v29, 0xfffff620
	v_cmp_lt_i32_e32 vcc, 0xfff, v27
	s_nop 1
	v_cndmask_b32_e32 v28, v28, v29, vcc
	v_mov_b32_e32 v29, 0xffffee00
	v_cmp_lt_i32_e32 vcc, 0x15ff, v27
	s_nop 1
	v_cndmask_b32_e32 v28, v28, v29, vcc
	v_mov_b32_e32 v29, 0x1620
	v_cmp_gt_i32_e64 s[30:31], v29, v27
	v_add_u32_e32 v28, v27, v28
	s_nop 0
	v_cndmask_b32_e64 v28, 0, v28, s[30:31]
	v_mad_u32_u24 v31, v26, s10, v28
	v_lshlrev_b32_e32 v31, 2, v31
	v_lshlrev_b32_e32 v32, 11, v27
	v_lshl_add_u32 v32, v26, 4, v32
	global_load_dword v34, v31, s[12:13]
	global_load_dword v35, v31, s[14:15]
	global_load_dword v36, v31, s[16:17]
	global_load_dword v37, v31, s[18:19]
	global_load_dword v38, v31, s[20:21]
	global_load_dword v39, v31, s[22:23]
	global_load_dword v40, v31, s[24:25]
	global_load_dword v41, v31, s[26:27]
	s_waitcnt vmcnt(8)
	v_cndmask_b32_e64 v12, 0, v12, s[28:29]
	v_cndmask_b32_e64 v13, 0, v13, s[28:29]
	v_cndmask_b32_e64 v14, 0, v14, s[28:29]
	v_cndmask_b32_e64 v15, 0, v15, s[28:29]
	v_cndmask_b32_e64 v16, 0, v16, s[28:29]
	v_cndmask_b32_e64 v17, 0, v17, s[28:29]
	v_cndmask_b32_e64 v18, 0, v18, s[28:29]
	v_cndmask_b32_e64 v19, 0, v19, s[28:29]
	v_cvt_pk_bf16_f32 v20, v12, v13
	v_cvt_pk_bf16_f32 v21, v14, v15
	v_cvt_pk_bf16_f32 v22, v16, v17
	v_cvt_pk_bf16_f32 v23, v18, v19
	global_store_dwordx4 v10, v[20:23], s[62:63]
	s_waitcnt vmcnt(1)
	s_mov_b64 s[38:39], exec
	s_and_b64 exec, exec, s[36:37]
	v_cndmask_b32_e64 v34, 0, v34, s[30:31]
	v_cndmask_b32_e64 v35, 0, v35, s[30:31]
	v_cndmask_b32_e64 v36, 0, v36, s[30:31]
	v_cndmask_b32_e64 v37, 0, v37, s[30:31]
	v_cndmask_b32_e64 v38, 0, v38, s[30:31]
	v_cndmask_b32_e64 v39, 0, v39, s[30:31]
	v_cndmask_b32_e64 v40, 0, v40, s[30:31]
	v_cndmask_b32_e64 v41, 0, v41, s[30:31]
	v_cvt_pk_bf16_f32 v44, v34, v35
	v_cvt_pk_bf16_f32 v45, v36, v37
	v_cvt_pk_bf16_f32 v46, v38, v39
	v_cvt_pk_bf16_f32 v47, v40, v41
	global_store_dwordx4 v32, v[44:47], s[62:63]
	s_mov_b64 exec, s[38:39]
	v_add_u32_e32 v1, s8, v24
	v_cmp_lt_i32_e32 vcc, s34, v1
	s_or_b64 s[2:3], vcc, s[2:3]
	s_andn2_b64 exec, exec, s[2:3]
	s_cbranch_execnz .Lcv_loop
